# v77 without the dispatch-code store-widening patches (smaller instruction footprint)
# speedup vs baseline: 1.0014x; 1.0014x over previous
.LBB0_90:
	v_mov_b32_e32 v136, s88
	ds_read_b32 v136, v136
	v_readlane_b32 s2, v254, 44
	v_mov_b32_e32 v151, v153
	s_mov_b64 s[58:59], -1
	s_mov_b64 s[56:57], 0
	s_waitcnt lgkmcnt(0)
	v_readfirstlane_b32 s48, v136
	v_mov_b32_e32 v136, s89
	ds_read_b32 v136, v136
	s_add_u32 s52, s48, 0x2100000
	s_waitcnt lgkmcnt(0)
	v_readfirstlane_b32 s49, v136
	v_mov_b32_e32 v136, s2
	ds_read_b32 v136, v136
	v_readlane_b32 s2, v254, 45
	s_addc_u32 s53, s49, 0
	s_add_u32 s46, s48, 0x158d0000
	s_addc_u32 s47, s49, 0
	s_waitcnt lgkmcnt(0)
	v_readfirstlane_b32 s42, v136
	v_mov_b32_e32 v136, s2
	ds_read_b32 v136, v136
	v_readlane_b32 s2, v254, 31
	s_add_u32 s40, s48, 0xc600000
	s_addc_u32 s41, s49, 0
	s_add_u32 s36, s48, 0xe700000
	s_waitcnt lgkmcnt(0)
	v_readfirstlane_b32 s43, v136
	v_mov_b32_e32 v136, s2
	ds_read_b32 v136, v136
	v_readlane_b32 s2, v254, 46
	s_addc_u32 s37, s49, 0
	s_add_u32 s34, s48, 0x6300000
	s_addc_u32 s35, s49, 0
	s_waitcnt lgkmcnt(0)
	v_readfirstlane_b32 s65, v136
	v_mov_b32_e32 v136, s2
	ds_read_b32 v136, v136
	v_readlane_b32 s2, v254, 39
	s_add_u32 s38, s48, 0x4200000
	s_addc_u32 s39, s49, 0
	s_add_u32 s50, s48, 0x15af4000
	s_waitcnt lgkmcnt(0)
	v_readfirstlane_b32 s66, v136
	v_mov_b32_e32 v136, s2
	ds_read_b32 v136, v136
	v_readlane_b32 s2, v254, 48
	s_addc_u32 s51, s49, 0
	s_lshl_b32 s62, s10, 8
	s_lshl_b32 s27, s67, 8
	s_waitcnt lgkmcnt(0)
	v_readfirstlane_b32 s44, v136
	v_mov_b32_e32 v136, s2
	v_readlane_b32 s2, v254, 40
	s_add_i32 s62, s62, s2
	s_ashr_i32 s2, s62, 13
	ds_read_b32 v136, v136
	s_mul_i32 s54, s2, 0x1800
	v_readlane_b32 s2, v254, 26
	s_ashr_i32 s55, s54, 31
	s_mul_i32 s2, s2, 0x12000
	s_add_u32 s2, s48, s2
	v_or_b32_e32 v138, s62, v157
	s_addc_u32 s3, s49, 0
	v_ashrrev_i32_e32 v139, 31, v138
	s_add_u32 s30, s2, 0x15ad0000
	s_waitcnt lgkmcnt(0)
	v_readfirstlane_b32 s45, v136
	v_lshlrev_b64 v[136:137], 13, v[138:139]
	v_add_u32_e32 v150, 0xffffc000, v138
	s_addc_u32 s31, s3, 0
	v_lshl_add_u64 v[148:149], s[52:53], 0, v[136:137]
	v_cmp_gt_i32_e64 s[10:11], s92, v138
	v_cmp_lt_i32_e64 s[8:9], s80, v138
	v_lshlrev_b64 v[146:147], 10, v[150:151]
	v_lshlrev_b64 v[142:143], 10, v[138:139]
	v_or_b32_e32 v136, s27, v161
	s_cmp_lg_u32 s79, 18
	s_cbranch_scc1 .Lrw_no
	v_lshlrev_b64 v[244:245], 11, v[138:139]
	v_lshl_add_u64 v[244:245], s[48:49], 0, v[244:245]
	v_mbcnt_lo_u32_b32 v246, -1, 0
	v_mbcnt_hi_u32_b32 v246, -1, v246
	v_and_b32_e32 v246, 16, v246
	v_lshrrev_b32_e32 v247, 1, v246
	v_add_u32_e32 v246, v246, v247
	v_and_b32_e32 v247, 0x3ff, v136
	v_lshl_add_u32 v246, v247, 1, v246
	v_mov_b32_e32 v247, 0
	v_lshl_add_u64 v[244:245], v[246:247], 0, v[244:245]
	s_ashr_i32 s2, s67, 2
	s_add_i32 s2, s2, 1
	s_mul_i32 s2, s2, 0x2100000
	s_mov_b32 s3, 0
	v_lshl_add_u64 v[244:245], v[244:245], 0, s[2:3]
	v_cvt_pk_f16_f32 v230, v124, v125
	v_cvt_pk_f16_f32 v231, v126, v127
	v_cvt_pk_f16_f32 v232, v120, v121
	v_cvt_pk_f16_f32 v233, v122, v123
	s_nop 1
	v_permlane16_swap_b32 v230, v232
	v_permlane16_swap_b32 v231, v233
	global_store_dwordx4 v[244:245], v[230:233], off
	v_cvt_pk_f16_f32 v234, v116, v117
	v_cvt_pk_f16_f32 v235, v118, v119
	v_cvt_pk_f16_f32 v236, v112, v113
	v_cvt_pk_f16_f32 v237, v114, v115
	v_add_co_u32_e32 v246, vcc, 0x100, v244
	v_addc_co_u32_e32 v247, vcc, 0, v245, vcc
	v_permlane16_swap_b32 v234, v236
	v_permlane16_swap_b32 v235, v237
	global_store_dwordx4 v[246:247], v[234:237], off
	v_cvt_pk_f16_f32 v230, v108, v109
	v_cvt_pk_f16_f32 v231, v110, v111
	v_cvt_pk_f16_f32 v232, v104, v105
	v_cvt_pk_f16_f32 v233, v106, v107
	v_add_co_u32_e32 v246, vcc, 0x8000, v244
	v_addc_co_u32_e32 v247, vcc, 0, v245, vcc
	v_permlane16_swap_b32 v230, v232
	v_permlane16_swap_b32 v231, v233
	global_store_dwordx4 v[246:247], v[230:233], off
	v_cvt_pk_f16_f32 v234, v100, v101
	v_cvt_pk_f16_f32 v235, v102, v103
	v_cvt_pk_f16_f32 v236, v96, v97
	v_cvt_pk_f16_f32 v237, v98, v99
	v_add_co_u32_e32 v246, vcc, 0x8100, v244
	v_addc_co_u32_e32 v247, vcc, 0, v245, vcc
	v_permlane16_swap_b32 v234, v236
	v_permlane16_swap_b32 v235, v237
	global_store_dwordx4 v[246:247], v[234:237], off
	v_cvt_pk_f16_f32 v230, v92, v93
	v_cvt_pk_f16_f32 v231, v94, v95
	v_cvt_pk_f16_f32 v232, v88, v89
	v_cvt_pk_f16_f32 v233, v90, v91
	v_add_co_u32_e32 v246, vcc, 0x10000, v244
	v_addc_co_u32_e32 v247, vcc, 0, v245, vcc
	v_permlane16_swap_b32 v230, v232
	v_permlane16_swap_b32 v231, v233
	global_store_dwordx4 v[246:247], v[230:233], off
	v_cvt_pk_f16_f32 v234, v84, v85
	v_cvt_pk_f16_f32 v235, v86, v87
	v_cvt_pk_f16_f32 v236, v80, v81
	v_cvt_pk_f16_f32 v237, v82, v83
	v_add_co_u32_e32 v246, vcc, 0x10100, v244
	v_addc_co_u32_e32 v247, vcc, 0, v245, vcc
	v_permlane16_swap_b32 v234, v236
	v_permlane16_swap_b32 v235, v237
	global_store_dwordx4 v[246:247], v[234:237], off
	v_cvt_pk_f16_f32 v230, v76, v77
	v_cvt_pk_f16_f32 v231, v78, v79
	v_cvt_pk_f16_f32 v232, v72, v73
	v_cvt_pk_f16_f32 v233, v74, v75
	v_add_co_u32_e32 v246, vcc, 0x18000, v244
	v_addc_co_u32_e32 v247, vcc, 0, v245, vcc
	v_permlane16_swap_b32 v230, v232
	v_permlane16_swap_b32 v231, v233
	global_store_dwordx4 v[246:247], v[230:233], off
	v_cvt_pk_f16_f32 v234, v68, v69
	v_cvt_pk_f16_f32 v235, v70, v71
	v_cvt_pk_f16_f32 v236, v64, v65
	v_cvt_pk_f16_f32 v237, v66, v67
	v_add_co_u32_e32 v246, vcc, 0x18100, v244
	v_addc_co_u32_e32 v247, vcc, 0, v245, vcc
	v_permlane16_swap_b32 v234, v236
	v_permlane16_swap_b32 v235, v237
	global_store_dwordx4 v[246:247], v[234:237], off
	v_cvt_pk_f16_f32 v230, v60, v61
	v_cvt_pk_f16_f32 v231, v62, v63
	v_cvt_pk_f16_f32 v232, v56, v57
	v_cvt_pk_f16_f32 v233, v58, v59
	v_add_co_u32_e32 v246, vcc, 0x40000, v244
	v_addc_co_u32_e32 v247, vcc, 0, v245, vcc
	v_permlane16_swap_b32 v230, v232
	v_permlane16_swap_b32 v231, v233
	global_store_dwordx4 v[246:247], v[230:233], off
	v_cvt_pk_f16_f32 v234, v52, v53
	v_cvt_pk_f16_f32 v235, v54, v55
	v_cvt_pk_f16_f32 v236, v48, v49
	v_cvt_pk_f16_f32 v237, v50, v51
	v_add_co_u32_e32 v246, vcc, 0x40100, v244
	v_addc_co_u32_e32 v247, vcc, 0, v245, vcc
	v_permlane16_swap_b32 v234, v236
	v_permlane16_swap_b32 v235, v237
	global_store_dwordx4 v[246:247], v[234:237], off
	v_cvt_pk_f16_f32 v230, v44, v45
	v_cvt_pk_f16_f32 v231, v46, v47
	v_cvt_pk_f16_f32 v232, v40, v41
	v_cvt_pk_f16_f32 v233, v42, v43
	v_add_co_u32_e32 v246, vcc, 0x48000, v244
	v_addc_co_u32_e32 v247, vcc, 0, v245, vcc
	v_permlane16_swap_b32 v230, v232
	v_permlane16_swap_b32 v231, v233
	global_store_dwordx4 v[246:247], v[230:233], off
	v_cvt_pk_f16_f32 v234, v36, v37
	v_cvt_pk_f16_f32 v235, v38, v39
	v_cvt_pk_f16_f32 v236, v32, v33
	v_cvt_pk_f16_f32 v237, v34, v35
	v_add_co_u32_e32 v246, vcc, 0x48100, v244
	v_addc_co_u32_e32 v247, vcc, 0, v245, vcc
	v_permlane16_swap_b32 v234, v236
	v_permlane16_swap_b32 v235, v237
	global_store_dwordx4 v[246:247], v[234:237], off
	v_cvt_pk_f16_f32 v230, v28, v29
	v_cvt_pk_f16_f32 v231, v30, v31
	v_cvt_pk_f16_f32 v232, v24, v25
	v_cvt_pk_f16_f32 v233, v26, v27
	v_add_co_u32_e32 v246, vcc, 0x50000, v244
	v_addc_co_u32_e32 v247, vcc, 0, v245, vcc
	v_permlane16_swap_b32 v230, v232
	v_permlane16_swap_b32 v231, v233
	global_store_dwordx4 v[246:247], v[230:233], off
	v_cvt_pk_f16_f32 v234, v20, v21
	v_cvt_pk_f16_f32 v235, v22, v23
	v_cvt_pk_f16_f32 v236, v16, v17
	v_cvt_pk_f16_f32 v237, v18, v19
	v_add_co_u32_e32 v246, vcc, 0x50100, v244
	v_addc_co_u32_e32 v247, vcc, 0, v245, vcc
	v_permlane16_swap_b32 v234, v236
	v_permlane16_swap_b32 v235, v237
	global_store_dwordx4 v[246:247], v[234:237], off
	v_cvt_pk_f16_f32 v230, v12, v13
	v_cvt_pk_f16_f32 v231, v14, v15
	v_cvt_pk_f16_f32 v232, v8, v9
	v_cvt_pk_f16_f32 v233, v10, v11
	v_add_co_u32_e32 v246, vcc, 0x58000, v244
	v_addc_co_u32_e32 v247, vcc, 0, v245, vcc
	v_permlane16_swap_b32 v230, v232
	v_permlane16_swap_b32 v231, v233
	global_store_dwordx4 v[246:247], v[230:233], off
	v_cvt_pk_f16_f32 v234, v4, v5
	v_cvt_pk_f16_f32 v235, v6, v7
	v_cvt_pk_f16_f32 v236, v0, v1
	v_cvt_pk_f16_f32 v237, v2, v3
	v_add_co_u32_e32 v246, vcc, 0x58100, v244
	v_addc_co_u32_e32 v247, vcc, 0, v245, vcc
	v_permlane16_swap_b32 v234, v236
	v_permlane16_swap_b32 v235, v237
	global_store_dwordx4 v[246:247], v[234:237], off
	s_branch .LBB0_1065
